# v44
# speedup vs baseline: 1.0052x; 1.0052x over previous
.LBB0_243:
	v_med3_f32 v3, v48, s87, v198
	v_med3_f32 v10, v58, s87, v198
	v_exp_f32_e32 v4, v3
	s_nop 7
	v_med3_f32 v3, v49, s87, v198
	v_exp_f32_e32 v131, v10
	v_med3_f32 v10, v59, s87, v198
	v_exp_f32_e32 v5, v3
	v_med3_f32 v3, v50, s87, v198
	v_exp_f32_e32 v132, v10
	v_med3_f32 v10, v60, s87, v198
	v_exp_f32_e32 v3, v3
	v_med3_f32 v6, v51, s87, v198
	v_exp_f32_e32 v12, v10
	v_med3_f32 v10, v61, s87, v198
	v_exp_f32_e32 v128, v6
	v_exp_f32_e32 v13, v10
	v_med3_f32 v10, v62, s87, v198
	v_med3_f32 v6, v52, s87, v198
	v_med3_f32 v7, v53, s87, v198
	v_exp_f32_e32 v60, v10
	v_med3_f32 v10, v63, s87, v198
	v_exp_f32_e32 v6, v6
	v_exp_f32_e32 v7, v7
	v_med3_f32 v8, v54, s87, v198
	v_exp_f32_e32 v61, v10
	v_pk_add_f32 v[10:11], v[4:5], 1.0 op_sel_hi:[1,0]
	v_exp_f32_e32 v129, v8
	v_med3_f32 v8, v55, s87, v198
	v_mul_f32_e32 v11, v10, v11
	v_add_f32_e32 v14, 1.0, v3
	v_exp_f32_e32 v130, v8
	v_mul_f32_e32 v62, v14, v11
	v_add_f32_e32 v14, 1.0, v128
	v_med3_f32 v8, v56, s87, v198
	v_med3_f32 v9, v57, s87, v198
	v_mul_f32_e32 v14, v14, v62
	v_exp_f32_e32 v8, v8
	v_exp_f32_e32 v9, v9
	v_rcp_f32_e32 v54, v14
	v_pk_add_f32 v[14:15], v[6:7], 1.0 op_sel_hi:[1,0]
	v_add_f32_e32 v48, 1.0, v129
	v_mul_f32_e32 v15, v14, v15
	v_mul_f32_e32 v133, v48, v15
	v_add_f32_e32 v48, 1.0, v130
	v_mul_f32_e32 v48, v48, v133
	v_rcp_f32_e32 v58, v48
	v_pk_add_f32 v[48:49], v[8:9], 1.0 op_sel_hi:[1,0]
	v_add_f32_e32 v50, 1.0, v131
	v_mul_f32_e32 v49, v48, v49
	v_mul_f32_e32 v135, v50, v49
	v_add_f32_e32 v50, 1.0, v132
	v_mul_f32_e32 v50, v50, v135
	v_rcp_f32_e32 v55, v50
	v_pk_add_f32 v[50:51], v[12:13], 1.0 op_sel_hi:[1,0]
	v_add_f32_e32 v52, 1.0, v60
	v_mul_f32_e32 v51, v50, v51
	v_mul_f32_e32 v137, v52, v51
	v_add_f32_e32 v52, 1.0, v61
	v_mul_f32_e32 v52, v52, v137
	v_rcp_f32_e32 v59, v52
	v_mov_b32_e32 v56, v58
	v_mov_b32_e32 v52, v54
	v_mov_b32_e32 v53, v55
	v_mov_b32_e32 v57, v59
	v_permlane32_swap_b32_e32 v56, v58
	v_permlane32_swap_b32_e32 v52, v54
	v_permlane32_swap_b32_e32 v53, v55
	v_permlane32_swap_b32_e32 v57, v59
	v_pk_mul_f32 v[52:53], v[52:53], v[54:55]
	v_pk_mul_f32 v[56:57], v[56:57], v[58:59]
	v_mul_f32_e32 v139, v127, v57
	v_mul_f32_e32 v140, v53, v139
	v_mul_f32_e32 v141, v56, v140
	v_cndmask_b32_e64 v54, v54, v52, s[6:7]
	v_mul_f32_e32 v54, v54, v141
	v_mul_f32_e32 v63, v4, v54
	v_mul_f32_e32 v4, v5, v54
	v_mul_f32_e32 v10, v10, v4
	v_mul_f32_e32 v3, v3, v54
	v_mul_f32_e32 v4, v128, v54
	v_mul_f32_e32 v3, v11, v3
	v_mul_f32_e32 v11, v62, v4
	v_cndmask_b32_e64 v4, v58, v56, s[6:7]
	v_mul_f32_e32 v4, v4, v140
	v_mul_f32_e32 v5, v7, v4
	v_mul_f32_e32 v54, v6, v4
	v_mul_f32_e32 v14, v14, v5
	v_mul_f32_e32 v5, v129, v4
	v_mul_f32_e32 v4, v130, v4
	v_mul_f32_e32 v58, v133, v4
	v_cndmask_b32_e64 v4, v55, v53, s[6:7]
	v_mul_f32_e32 v4, v4, v139
	v_mul_f32_e32 v15, v15, v5
	v_mul_f32_e32 v5, v9, v4
	v_mul_f32_e32 v55, v8, v4
	v_mul_f32_e32 v48, v48, v5
	v_mul_f32_e32 v5, v131, v4
	v_mul_f32_e32 v4, v132, v4
	v_mul_f32_e32 v62, v135, v4
	v_cndmask_b32_e64 v4, v59, v57, s[6:7]
	v_mul_f32_e32 v59, v127, v4
	s_nop 0
	v_mul_f32_e32 v49, v49, v5
	s_nop 0
	v_cvt_pk_bf16_f32 v8, v63, v10
	v_cvt_pk_bf16_f32 v10, v54, v14
	s_nop 0
	v_cvt_pk_bf16_f32 v9, v3, v11
	v_cvt_pk_bf16_f32 v11, v15, v58
	v_mul_f32_e32 v127, v12, v59
	s_waitcnt lgkmcnt(0)
	v_mfma_f32_32x32x16_bf16 v[16:31], v[8:11], v[228:231], v[16:31]
	s_nop 0
	v_mul_f32_e32 v12, v60, v59
	v_mul_f32_e32 v15, v51, v12
	v_mul_f32_e32 v12, v61, v59
	v_mul_f32_e32 v3, v13, v59
	v_mul_f32_e32 v3, v50, v3
	s_waitcnt lgkmcnt(0)
	v_mfma_f32_32x32x16_bf16 v[32:47], v[8:11], v[232:235], v[32:47]
	s_nop 0
	v_mul_f32_e32 v11, v137, v12
	v_cvt_pk_bf16_f32 v8, v55, v48
	v_cvt_pk_bf16_f32 v9, v49, v62
	v_cvt_pk_bf16_f32 v10, v127, v3
	v_cvt_pk_bf16_f32 v11, v15, v11
	s_nop 1
	s_waitcnt lgkmcnt(0)
	v_mfma_f32_32x32x16_bf16 v[16:31], v[8:11], v[236:239], v[16:31]
	s_nop 0
	s_nop 0
	s_waitcnt lgkmcnt(0)
	v_mfma_f32_32x32x16_bf16 v[32:47], v[8:11], v[240:243], v[32:47]
	v_mul_f32_e32 v127, v141, v52
